# combo8: combo6 + P0 weight-transpose items with a norm gain (w_up, w_ple_gate): all 32 weight loads and 32 gain loads issued up front and consumed with counted vmcnt, instead of one load round trip pe
# speedup vs baseline: 1.0046x; 1.0046x over previous
; #define LAS __attribute__((address_space(3)))
; template <int MODE> __device__ __forceinline__ void transpose_item(const float* W, int K, int Nsrc, int Ndst, bf16_t* WT, LAS float* scr, int item, int lane, const float* kgain = nullptr) {
;     const int nblk = Ndst / 32, kb = item / nblk, nb = item % nblk, k0 = 64 * kb, n0 = 32 * nb;
;     const int sc = srccol<MODE>(n0 + (lane & 31));
; #pragma unroll
;     for (int i = 0; i < 32; ++i) { const int kk = 2 * i + (lane >> 5); scr[kk * 33 + (lane & 31)] = W[(size_t)(k0 + kk) * Nsrc + sc] * (kgain ? kgain[k0 + kk] : 1.0f); }
.LBB0_14:
	s_andn2_b64 vcc, exec, s[0:1]
	s_cbranch_vccnz .LBB0_80
	s_mov_b64 s[0:1], s[46:47]
	s_load_dwordx2 s[4:5], s[0:1], 0x80
	s_mov_b64 s[0:1], s[46:47]
	s_mov_b32 s24, -1
	s_lshl_b64 s[22:23], s[20:21], 22
	v_mbcnt_lo_u32_b32 v2, s24, 0
	v_mbcnt_hi_u32_b32 v10, s24, v2
	s_mov_b64 s[24:25], s[46:47]
	s_load_dwordx2 s[40:41], s[24:25], 0x78
	s_waitcnt lgkmcnt(0)
	s_add_u32 s4, s4, s22
	s_addc_u32 s5, s5, s23
	s_lshl_b32 s22, s20, 10
	s_ashr_i32 s23, s22, 31
	s_lshl_b64 s[24:25], s[22:23], 2
	s_add_u32 s42, s40, s24
	s_addc_u32 s43, s41, s25
	s_lshl_b32 s23, s20, 11
	s_sub_i32 s23, s27, s23
	s_sub_i32 s22, s3, s22
	s_addk_i32 s23, 0xdb00
	s_add_i32 s22, s22, 0xfffdb000
	s_and_b32 s38, s23, 0xfc0
	s_and_b32 s37, s22, 0x3e0
	v_and_b32_e32 v12, 31, v10
	v_ashrrev_i32_e32 v13, 5, v10
	v_or_b32_e32 v2, s37, v12
	v_add_u32_e32 v8, s38, v13
	v_lshlrev_b32_e32 v2, 2, v2
	v_ashrrev_i32_e32 v9, 31, v8
	v_lshl_add_u64 v[4:5], s[4:5], 0, v[2:3]
	v_lshlrev_b64 v[14:15], 12, v[8:9]
	v_lshl_add_u64 v[14:15], v[4:5], 0, v[14:15]
	v_lshl_add_u64 v[6:7], v[8:9], 2, s[42:43]
	s_load_dwordx2 s[22:23], s[46:47], 0x98
	v_lshl_add_u32 v12, v12, 2, s2
	v_mul_lo_u32 v2, v13, s29
	v_add_u32_e32 v2, v12, v2
	s_cmp_eq_u64 s[40:41], 0
	s_mov_b32 s98, 0x2000
	s_mov_b32 s99, 0
	v_mov_b32_e32 v54, 1.0
	v_mov_b32_e32 v55, 1.0
	v_mov_b32_e32 v56, 1.0
	v_mov_b32_e32 v57, 1.0
	v_mov_b32_e32 v58, 1.0
	v_mov_b32_e32 v59, 1.0
	v_mov_b32_e32 v60, 1.0
	v_mov_b32_e32 v61, 1.0
	v_mov_b32_e32 v62, 1.0
	v_mov_b32_e32 v63, 1.0
	v_mov_b32_e32 v64, 1.0
	v_mov_b32_e32 v65, 1.0
	v_mov_b32_e32 v66, 1.0
	v_mov_b32_e32 v67, 1.0
	v_mov_b32_e32 v68, 1.0
	v_mov_b32_e32 v69, 1.0
	v_mov_b32_e32 v70, 1.0
	v_mov_b32_e32 v71, 1.0
	v_mov_b32_e32 v72, 1.0
	v_mov_b32_e32 v73, 1.0
	v_mov_b32_e32 v74, 1.0
	v_mov_b32_e32 v75, 1.0
	v_mov_b32_e32 v76, 1.0
	v_mov_b32_e32 v77, 1.0
	v_mov_b32_e32 v78, 1.0
	v_mov_b32_e32 v79, 1.0
	v_mov_b32_e32 v80, 1.0
	v_mov_b32_e32 v81, 1.0
	v_mov_b32_e32 v82, 1.0
	v_mov_b32_e32 v83, 1.0
	v_mov_b32_e32 v84, 1.0
	v_mov_b32_e32 v85, 1.0
	s_cbranch_scc1 .Lkg_gt_nogain
	global_load_dword v54, v[6:7], off
	global_load_dword v55, v[6:7], off offset:8
	global_load_dword v56, v[6:7], off offset:16
	global_load_dword v57, v[6:7], off offset:24
	global_load_dword v58, v[6:7], off offset:32
	global_load_dword v59, v[6:7], off offset:40
	global_load_dword v60, v[6:7], off offset:48
	global_load_dword v61, v[6:7], off offset:56
	global_load_dword v62, v[6:7], off offset:64
	global_load_dword v63, v[6:7], off offset:72
	global_load_dword v64, v[6:7], off offset:80
	global_load_dword v65, v[6:7], off offset:88
	global_load_dword v66, v[6:7], off offset:96
	global_load_dword v67, v[6:7], off offset:104
	global_load_dword v68, v[6:7], off offset:112
	global_load_dword v69, v[6:7], off offset:120
	global_load_dword v70, v[6:7], off offset:128
	global_load_dword v71, v[6:7], off offset:136
	global_load_dword v72, v[6:7], off offset:144
	global_load_dword v73, v[6:7], off offset:152
	global_load_dword v74, v[6:7], off offset:160
	global_load_dword v75, v[6:7], off offset:168
	global_load_dword v76, v[6:7], off offset:176
	global_load_dword v77, v[6:7], off offset:184
	global_load_dword v78, v[6:7], off offset:192
	global_load_dword v79, v[6:7], off offset:200
	global_load_dword v80, v[6:7], off offset:208
	global_load_dword v81, v[6:7], off offset:216
	global_load_dword v82, v[6:7], off offset:224
	global_load_dword v83, v[6:7], off offset:232
	global_load_dword v84, v[6:7], off offset:240
	global_load_dword v85, v[6:7], off offset:248
.Lkg_gt_nogain:
	global_load_dword v86, v[14:15], off
	v_lshl_add_u64 v[14:15], v[14:15], 0, s[98:99]
	global_load_dword v87, v[14:15], off
	v_lshl_add_u64 v[14:15], v[14:15], 0, s[98:99]
	global_load_dword v88, v[14:15], off
	v_lshl_add_u64 v[14:15], v[14:15], 0, s[98:99]
	global_load_dword v89, v[14:15], off
	v_lshl_add_u64 v[14:15], v[14:15], 0, s[98:99]
	global_load_dword v90, v[14:15], off
	v_lshl_add_u64 v[14:15], v[14:15], 0, s[98:99]
	global_load_dword v91, v[14:15], off
	v_lshl_add_u64 v[14:15], v[14:15], 0, s[98:99]
	global_load_dword v92, v[14:15], off
	v_lshl_add_u64 v[14:15], v[14:15], 0, s[98:99]
	global_load_dword v93, v[14:15], off
	v_lshl_add_u64 v[14:15], v[14:15], 0, s[98:99]
	global_load_dword v94, v[14:15], off
	v_lshl_add_u64 v[14:15], v[14:15], 0, s[98:99]
	global_load_dword v95, v[14:15], off
	v_lshl_add_u64 v[14:15], v[14:15], 0, s[98:99]
	global_load_dword v96, v[14:15], off
	v_lshl_add_u64 v[14:15], v[14:15], 0, s[98:99]
	global_load_dword v97, v[14:15], off
	v_lshl_add_u64 v[14:15], v[14:15], 0, s[98:99]
	global_load_dword v98, v[14:15], off
	v_lshl_add_u64 v[14:15], v[14:15], 0, s[98:99]
	global_load_dword v99, v[14:15], off
	v_lshl_add_u64 v[14:15], v[14:15], 0, s[98:99]
	global_load_dword v100, v[14:15], off
	v_lshl_add_u64 v[14:15], v[14:15], 0, s[98:99]
	global_load_dword v101, v[14:15], off
	v_lshl_add_u64 v[14:15], v[14:15], 0, s[98:99]
	global_load_dword v102, v[14:15], off
	v_lshl_add_u64 v[14:15], v[14:15], 0, s[98:99]
	global_load_dword v103, v[14:15], off
	v_lshl_add_u64 v[14:15], v[14:15], 0, s[98:99]
	global_load_dword v104, v[14:15], off
	v_lshl_add_u64 v[14:15], v[14:15], 0, s[98:99]
	global_load_dword v105, v[14:15], off
	v_lshl_add_u64 v[14:15], v[14:15], 0, s[98:99]
	global_load_dword v106, v[14:15], off
	v_lshl_add_u64 v[14:15], v[14:15], 0, s[98:99]
	global_load_dword v107, v[14:15], off
	v_lshl_add_u64 v[14:15], v[14:15], 0, s[98:99]
	global_load_dword v108, v[14:15], off
	v_lshl_add_u64 v[14:15], v[14:15], 0, s[98:99]
	global_load_dword v109, v[14:15], off
	v_lshl_add_u64 v[14:15], v[14:15], 0, s[98:99]
	global_load_dword v110, v[14:15], off
	v_lshl_add_u64 v[14:15], v[14:15], 0, s[98:99]
	global_load_dword v111, v[14:15], off
	v_lshl_add_u64 v[14:15], v[14:15], 0, s[98:99]
	global_load_dword v112, v[14:15], off
	v_lshl_add_u64 v[14:15], v[14:15], 0, s[98:99]
	global_load_dword v113, v[14:15], off
	v_lshl_add_u64 v[14:15], v[14:15], 0, s[98:99]
	global_load_dword v114, v[14:15], off
	v_lshl_add_u64 v[14:15], v[14:15], 0, s[98:99]
	global_load_dword v115, v[14:15], off
	v_lshl_add_u64 v[14:15], v[14:15], 0, s[98:99]
	global_load_dword v116, v[14:15], off
	v_lshl_add_u64 v[14:15], v[14:15], 0, s[98:99]
	global_load_dword v117, v[14:15], off
	s_waitcnt vmcnt(31)
; #define LAS __attribute__((address_space(3)))
; __device__ __forceinline__ unsigned pk2(float lo, float hi) { f32x2_t v = {lo, hi}; bf16x2_t b = __builtin_convertvector(v, bf16x2_t); return __builtin_bit_cast(unsigned, b); }
; template <int MODE> __device__ __forceinline__ void transpose_item(const float* W, int K, int Nsrc, int Ndst, bf16_t* WT, LAS float* scr, int item, int lane, const float* kgain = nullptr) {
;     ...
;     for (int i = 0; i < 32; ++i) { const int kk = 2 * i + (lane >> 5); scr[kk * 33 + (lane & 31)] = W[(size_t)(k0 + kk) * Nsrc + sc] * (kgain ? kgain[k0 + kk] : 1.0f); }
;     asm volatile("s_waitcnt lgkmcnt(0)" ::: "memory");
;     const int c = lane & 7;
; #pragma unroll
;     for (int j = 0; j < 4; ++j) { const int n = (lane >> 3) + 8 * j; const LAS float* s = scr + (8 * c) * 33 + n;
;         u32x4 o; o.x = pk2(s[0 * 33], s[1 * 33]); o.y = pk2(s[2 * 33], s[3 * 33]); o.z = pk2(s[4 * 33], s[5 * 33]); o.w = pk2(s[6 * 33], s[7 * 33]);
;         *(u32x4*)(WT + (size_t)(n0 + n) * K + k0 + 8 * c) = o; }
;     asm volatile("s_waitcnt lgkmcnt(0)" ::: "memory");
; }
	v_mul_f32_e32 v86, v86, v54
	ds_write_b32 v2, v86
	s_waitcnt vmcnt(30)
	v_mul_f32_e32 v87, v87, v55
	ds_write_b32 v2, v87 offset:264
	s_waitcnt vmcnt(29)
	v_mul_f32_e32 v88, v88, v56
	ds_write_b32 v2, v88 offset:528
	s_waitcnt vmcnt(28)
	v_mul_f32_e32 v89, v89, v57
	ds_write_b32 v2, v89 offset:792
	s_waitcnt vmcnt(27)
	v_mul_f32_e32 v90, v90, v58
	ds_write_b32 v2, v90 offset:1056
	s_waitcnt vmcnt(26)
	v_mul_f32_e32 v91, v91, v59
	ds_write_b32 v2, v91 offset:1320
	s_waitcnt vmcnt(25)
	v_mul_f32_e32 v92, v92, v60
	ds_write_b32 v2, v92 offset:1584
	s_waitcnt vmcnt(24)
	v_mul_f32_e32 v93, v93, v61
	ds_write_b32 v2, v93 offset:1848
	s_waitcnt vmcnt(23)
	v_mul_f32_e32 v94, v94, v62
	ds_write_b32 v2, v94 offset:2112
	s_waitcnt vmcnt(22)
	v_mul_f32_e32 v95, v95, v63
	ds_write_b32 v2, v95 offset:2376
	s_waitcnt vmcnt(21)
	v_mul_f32_e32 v96, v96, v64
	ds_write_b32 v2, v96 offset:2640
	s_waitcnt vmcnt(20)
	v_mul_f32_e32 v97, v97, v65
	ds_write_b32 v2, v97 offset:2904
	s_waitcnt vmcnt(19)
	v_mul_f32_e32 v98, v98, v66
	ds_write_b32 v2, v98 offset:3168
	s_waitcnt vmcnt(18)
	v_mul_f32_e32 v99, v99, v67
	ds_write_b32 v2, v99 offset:3432
	s_waitcnt vmcnt(17)
	v_mul_f32_e32 v100, v100, v68
	ds_write_b32 v2, v100 offset:3696
	s_waitcnt vmcnt(16)
	v_mul_f32_e32 v101, v101, v69
	ds_write_b32 v2, v101 offset:3960
	s_waitcnt vmcnt(15)
	v_mul_f32_e32 v102, v102, v70
	ds_write_b32 v2, v102 offset:4224
	s_waitcnt vmcnt(14)
	v_mul_f32_e32 v103, v103, v71
	ds_write_b32 v2, v103 offset:4488
	s_waitcnt vmcnt(13)
	v_mul_f32_e32 v104, v104, v72
	ds_write_b32 v2, v104 offset:4752
	s_waitcnt vmcnt(12)
	v_mul_f32_e32 v105, v105, v73
	ds_write_b32 v2, v105 offset:5016
	s_waitcnt vmcnt(11)
	v_mul_f32_e32 v106, v106, v74
	ds_write_b32 v2, v106 offset:5280
	s_waitcnt vmcnt(10)
	v_mul_f32_e32 v107, v107, v75
	ds_write_b32 v2, v107 offset:5544
	s_waitcnt vmcnt(9)
	v_mul_f32_e32 v108, v108, v76
	ds_write_b32 v2, v108 offset:5808
	s_waitcnt vmcnt(8)
	v_mul_f32_e32 v109, v109, v77
	ds_write_b32 v2, v109 offset:6072
	s_waitcnt vmcnt(7)
	v_mul_f32_e32 v110, v110, v78
	ds_write_b32 v2, v110 offset:6336
	s_waitcnt vmcnt(6)
	v_mul_f32_e32 v111, v111, v79
	ds_write_b32 v2, v111 offset:6600
	s_waitcnt vmcnt(5)
	v_mul_f32_e32 v112, v112, v80
	ds_write_b32 v2, v112 offset:6864
	s_waitcnt vmcnt(4)
	v_mul_f32_e32 v113, v113, v81
	ds_write_b32 v2, v113 offset:7128
	s_waitcnt vmcnt(3)
	v_mul_f32_e32 v114, v114, v82
	ds_write_b32 v2, v114 offset:7392
	s_waitcnt vmcnt(2)
	v_mul_f32_e32 v115, v115, v83
	ds_write_b32 v2, v115 offset:7656
	s_waitcnt vmcnt(1)
	v_mul_f32_e32 v116, v116, v84
	ds_write_b32 v2, v116 offset:7920
	s_waitcnt vmcnt(0)
	v_mul_f32_e32 v117, v117, v85
	ds_write_b32 v2, v117 offset:8184
.LBB0_79:
	s_lshl_b64 s[0:1], s[20:21], 21
	s_waitcnt lgkmcnt(0)
	s_add_u32 s0, s22, s0
	s_addc_u32 s1, s23, s1
	v_lshlrev_b32_e32 v2, 3, v10
	s_lshl_b32 s4, s38, 1
	v_and_b32_e32 v2, 56, v2
	s_add_u32 s0, s0, s4
	v_ashrrev_i32_e32 v26, 3, v10
	v_mul_u32_u24_e32 v6, 0x84, v2
	s_addc_u32 s1, s1, 0
	v_lshlrev_b32_e32 v2, 1, v2
	v_lshl_add_u64 v[4:5], s[0:1], 0, v[2:3]
	v_lshlrev_b32_e32 v2, 2, v26
	s_waitcnt lgkmcnt(0)
	v_add3_u32 v2, s2, v6, v2
	ds_read2_b32 v[8:9], v2 offset0:33 offset1:41
	ds_read2_b32 v[10:11], v2 offset1:8
	ds_read2_b32 v[12:13], v2 offset0:66 offset1:74
	ds_read2_b32 v[14:15], v2 offset0:99 offset1:107
	ds_read2_b32 v[16:17], v2 offset0:132 offset1:140
	ds_read2_b32 v[18:19], v2 offset0:165 offset1:173
	ds_read2_b32 v[20:21], v2 offset0:198 offset1:206
	ds_read2_b32 v[22:23], v2 offset0:231 offset1:239
	v_add_u32_e32 v26, s37, v26
	v_ashrrev_i32_e32 v27, 31, v26
	v_lshl_add_u64 v[24:25], v[4:5], 0, s[8:9]
	v_lshlrev_b64 v[28:29], 11, v[26:27]
	s_waitcnt lgkmcnt(6)
	v_cvt_pk_bf16_f32 v4, v10, v8
	s_waitcnt lgkmcnt(4)
	v_cvt_pk_bf16_f32 v5, v12, v14
	s_waitcnt lgkmcnt(2)
	v_cvt_pk_bf16_f32 v6, v16, v18
	s_waitcnt lgkmcnt(0)
	v_cvt_pk_bf16_f32 v7, v20, v22
	v_lshl_add_u64 v[28:29], v[24:25], 0, v[28:29]
	v_add_u32_e32 v8, 8, v26
	global_store_dwordx4 v[28:29], v[4:7], off
	s_nop 1
	v_cvt_pk_bf16_f32 v4, v11, v9
	v_ashrrev_i32_e32 v9, 31, v8
	v_cvt_pk_bf16_f32 v5, v13, v15
	v_cvt_pk_bf16_f32 v6, v17, v19
	v_cvt_pk_bf16_f32 v7, v21, v23
	v_lshlrev_b64 v[8:9], 11, v[8:9]
	ds_read2_b32 v[10:11], v2 offset0:49 offset1:57
	ds_read2_b32 v[12:13], v2 offset0:16 offset1:24
	ds_read2_b32 v[14:15], v2 offset0:82 offset1:90
	ds_read2_b32 v[16:17], v2 offset0:115 offset1:123
	ds_read2_b32 v[18:19], v2 offset0:148 offset1:156
	ds_read2_b32 v[20:21], v2 offset0:181 offset1:189
	ds_read2_b32 v[22:23], v2 offset0:214 offset1:222
	ds_read2_b32 v[28:29], v2 offset0:247 offset1:255
	v_lshl_add_u64 v[8:9], v[24:25], 0, v[8:9]
	global_store_dwordx4 v[8:9], v[4:7], off
	v_add_u32_e32 v8, 16, v26
	v_ashrrev_i32_e32 v9, 31, v8
	v_lshlrev_b64 v[8:9], 11, v[8:9]
	s_waitcnt lgkmcnt(6)
	v_cvt_pk_bf16_f32 v4, v12, v10
	s_waitcnt lgkmcnt(4)
	v_cvt_pk_bf16_f32 v5, v14, v16
	s_waitcnt lgkmcnt(2)
	v_cvt_pk_bf16_f32 v6, v18, v20
	s_waitcnt lgkmcnt(0)
	v_cvt_pk_bf16_f32 v7, v22, v28
	v_lshl_add_u64 v[8:9], v[24:25], 0, v[8:9]
	global_store_dwordx4 v[8:9], v[4:7], off
	v_add_u32_e32 v8, 24, v26
	v_ashrrev_i32_e32 v9, 31, v8
	v_lshlrev_b64 v[8:9], 11, v[8:9]
	v_cvt_pk_bf16_f32 v4, v13, v11
	v_cvt_pk_bf16_f32 v5, v15, v17
	v_cvt_pk_bf16_f32 v6, v19, v21
	v_cvt_pk_bf16_f32 v7, v23, v29
	v_lshl_add_u64 v[8:9], v[24:25], 0, v[8:9]
	global_store_dwordx4 v[8:9], v[4:7], off
	s_waitcnt lgkmcnt(0)

; #define LAS __attribute__((address_space(3)))
; template <int MODE> __device__ __forceinline__ int srccol(int n) {
;     if (MODE == 1) {
;         const int ct = n & 255, lg = (n & ~255) + ((ct >> 5) & 3) * 64 + (ct >> 7) * 32 + (ct & 31);
;         return lg < 2432 ? lg : lg + 6; }
;     if (MODE == 2) { const int pn = n >> 8, j = n & 255; return j < 128 ? 128 * pn + j : DFF + 128 * pn + (j - 128); }
;     return n;
; }
; template <int MODE> __device__ __forceinline__ void transpose_item(const float* W, int K, int Nsrc, int Ndst, bf16_t* WT, LAS float* scr, int item, int lane, const float* kgain = nullptr) {
;     const int nblk = Ndst / 32, kb = item / nblk, nb = item % nblk, k0 = 64 * kb, n0 = 32 * nb;
;     const int sc = srccol<MODE>(n0 + (lane & 31));
; #pragma unroll
;     for (int i = 0; i < 32; ++i) { const int kk = 2 * i + (lane >> 5); scr[kk * 33 + (lane & 31)] = W[(size_t)(k0 + kk) * Nsrc + sc] * (kgain ? kgain[k0 + kk] : 1.0f); }
.LBB0_84:
	s_andn2_b64 vcc, exec, s[0:1]
	s_cbranch_vccnz .LBB0_150
	s_mov_b64 s[0:1], s[46:47]
	s_load_dwordx2 s[4:5], s[0:1], 0x58
	s_mul_i32 s22, s20, 0x1600000
	s_mov_b64 s[0:1], s[46:47]
	s_mul_hi_i32 s21, s20, 0x1600000
	s_waitcnt lgkmcnt(0)
	s_add_u32 s4, s4, s22
	s_mov_b32 s22, -1
	s_addc_u32 s5, s5, s21
	v_mbcnt_lo_u32_b32 v2, s22, 0
	v_mbcnt_hi_u32_b32 v10, s22, v2
	s_mov_b64 s[22:23], s[46:47]
	s_load_dwordx2 s[22:23], s[22:23], 0x50
	s_lshl_b32 s24, s20, 10
	s_ashr_i32 s25, s24, 31
	s_lshl_b64 s[24:25], s[24:25], 2
	v_and_b32_e32 v11, 31, v10
	s_waitcnt lgkmcnt(0)
	s_add_u32 s38, s22, s24
	s_addc_u32 s39, s23, s25
	s_add_i32 s21, s36, 0xf700
	s_and_b32 s24, s21, 0xffff
	s_mul_i32 s24, s24, 0xba2f
	s_lshr_b32 s24, s24, 23
	s_mul_i32 s25, s24, 0xb0
	s_sub_i32 s25, s21, s25
	s_lshl_b32 s37, s25, 5
	s_lshl_b32 s21, s24, 6
	s_and_b32 s24, s37, 0xe0
	s_cmpk_lt_u32 s24, 0x80
	v_or_b32_e32 v2, s24, v11
	s_cselect_b64 vcc, -1, 0
	s_lshl_b32 s24, s25, 4
	s_and_b32 s24, s24, 0xf80
	v_or_b32_e32 v4, s24, v2
	s_addk_i32 s24, 0xa80
	v_add_u32_e32 v2, s24, v2
	v_cndmask_b32_e32 v2, v2, v4, vcc
	v_ashrrev_i32_e32 v12, 5, v10
	v_lshlrev_b32_e32 v2, 2, v2
	v_lshl_add_u64 v[4:5], s[4:5], 0, v[2:3]
	v_add_u32_e32 v6, s21, v12
	v_ashrrev_i32_e32 v7, 31, v6
	v_lshl_add_u64 v[8:9], v[6:7], 2, s[38:39]
	v_mad_i64_i32 v[14:15], s[0:1], v6, s31, v[4:5]
	v_lshl_add_u32 v11, v11, 2, s2
	v_mul_lo_u32 v2, v12, s29
	v_add_u32_e32 v2, v11, v2
	s_cmp_eq_u64 s[22:23], 0
	s_load_dwordx2 s[22:23], s[46:47], 0x98
	s_mov_b32 s98, 0xb000
	s_mov_b32 s99, 0
	v_mov_b32_e32 v54, 1.0
	v_mov_b32_e32 v55, 1.0
	v_mov_b32_e32 v56, 1.0
	v_mov_b32_e32 v57, 1.0
	v_mov_b32_e32 v58, 1.0
	v_mov_b32_e32 v59, 1.0
	v_mov_b32_e32 v60, 1.0
	v_mov_b32_e32 v61, 1.0
	v_mov_b32_e32 v62, 1.0
	v_mov_b32_e32 v63, 1.0
	v_mov_b32_e32 v64, 1.0
	v_mov_b32_e32 v65, 1.0
	v_mov_b32_e32 v66, 1.0
	v_mov_b32_e32 v67, 1.0
	v_mov_b32_e32 v68, 1.0
	v_mov_b32_e32 v69, 1.0
	v_mov_b32_e32 v70, 1.0
	v_mov_b32_e32 v71, 1.0
	v_mov_b32_e32 v72, 1.0
	v_mov_b32_e32 v73, 1.0
	v_mov_b32_e32 v74, 1.0
	v_mov_b32_e32 v75, 1.0
	v_mov_b32_e32 v76, 1.0
	v_mov_b32_e32 v77, 1.0
	v_mov_b32_e32 v78, 1.0
	v_mov_b32_e32 v79, 1.0
	v_mov_b32_e32 v80, 1.0
	v_mov_b32_e32 v81, 1.0
	v_mov_b32_e32 v82, 1.0
	v_mov_b32_e32 v83, 1.0
	v_mov_b32_e32 v84, 1.0
	v_mov_b32_e32 v85, 1.0
	s_cbranch_scc1 .Lkg_up_nogain
	global_load_dword v54, v[8:9], off
	global_load_dword v55, v[8:9], off offset:8
	global_load_dword v56, v[8:9], off offset:16
	global_load_dword v57, v[8:9], off offset:24
	global_load_dword v58, v[8:9], off offset:32
	global_load_dword v59, v[8:9], off offset:40
	global_load_dword v60, v[8:9], off offset:48
	global_load_dword v61, v[8:9], off offset:56
	global_load_dword v62, v[8:9], off offset:64
	global_load_dword v63, v[8:9], off offset:72
	global_load_dword v64, v[8:9], off offset:80
	global_load_dword v65, v[8:9], off offset:88
	global_load_dword v66, v[8:9], off offset:96
	global_load_dword v67, v[8:9], off offset:104
	global_load_dword v68, v[8:9], off offset:112
	global_load_dword v69, v[8:9], off offset:120
	global_load_dword v70, v[8:9], off offset:128
	global_load_dword v71, v[8:9], off offset:136
	global_load_dword v72, v[8:9], off offset:144
	global_load_dword v73, v[8:9], off offset:152
	global_load_dword v74, v[8:9], off offset:160
	global_load_dword v75, v[8:9], off offset:168
	global_load_dword v76, v[8:9], off offset:176
	global_load_dword v77, v[8:9], off offset:184
	global_load_dword v78, v[8:9], off offset:192
	global_load_dword v79, v[8:9], off offset:200
	global_load_dword v80, v[8:9], off offset:208
	global_load_dword v81, v[8:9], off offset:216
	global_load_dword v82, v[8:9], off offset:224
	global_load_dword v83, v[8:9], off offset:232
	global_load_dword v84, v[8:9], off offset:240
	global_load_dword v85, v[8:9], off offset:248

; #define LAS __attribute__((address_space(3)))
; __device__ __forceinline__ unsigned pk2(float lo, float hi) { f32x2_t v = {lo, hi}; bf16x2_t b = __builtin_convertvector(v, bf16x2_t); return __builtin_bit_cast(unsigned, b); }
; template <int MODE> __device__ __forceinline__ void transpose_item(const float* W, int K, int Nsrc, int Ndst, bf16_t* WT, LAS float* scr, int item, int lane, const float* kgain = nullptr) {
;     ...
;     asm volatile("s_waitcnt lgkmcnt(0)" ::: "memory");
;     const int c = lane & 7;
; #pragma unroll
;     for (int j = 0; j < 4; ++j) { const int n = (lane >> 3) + 8 * j; const LAS float* s = scr + (8 * c) * 33 + n;
;         u32x4 o; o.x = pk2(s[0 * 33], s[1 * 33]); o.y = pk2(s[2 * 33], s[3 * 33]); o.z = pk2(s[4 * 33], s[5 * 33]); o.w = pk2(s[6 * 33], s[7 * 33]);
;         *(u32x4*)(WT + (size_t)(n0 + n) * K + k0 + 8 * c) = o; }
;     asm volatile("s_waitcnt lgkmcnt(0)" ::: "memory");
; }
.LBB0_149:
	s_and_b32 s4, s37, 0xffe0
	s_mul_i32 s1, s20, 0xb00000
	s_mul_hi_i32 s0, s20, 0xb00000
	s_waitcnt lgkmcnt(0)
	s_add_u32 s1, s22, s1
	s_addc_u32 s5, s23, s0
	s_and_b32 s0, 0xffff, s21
	v_lshlrev_b32_e32 v2, 3, v10
	s_lshl_b32 s0, s0, 1
	v_and_b32_e32 v2, 56, v2
	s_add_u32 s0, s1, s0
	v_ashrrev_i32_e32 v26, 3, v10
	v_mul_u32_u24_e32 v6, 0x84, v2
	s_addc_u32 s1, s5, 0
	v_lshlrev_b32_e32 v2, 1, v2
	v_lshl_add_u64 v[4:5], s[0:1], 0, v[2:3]
	v_lshlrev_b32_e32 v2, 2, v26
	s_waitcnt lgkmcnt(0)
	v_add3_u32 v2, s2, v6, v2
	ds_read2_b32 v[8:9], v2 offset0:33 offset1:41
	ds_read2_b32 v[10:11], v2 offset1:8
	ds_read2_b32 v[12:13], v2 offset0:66 offset1:74
	ds_read2_b32 v[14:15], v2 offset0:99 offset1:107
	ds_read2_b32 v[16:17], v2 offset0:132 offset1:140
	ds_read2_b32 v[18:19], v2 offset0:165 offset1:173
	ds_read2_b32 v[20:21], v2 offset0:198 offset1:206
	ds_read2_b32 v[22:23], v2 offset0:231 offset1:239
	v_add_u32_e32 v26, s4, v26
	v_ashrrev_i32_e32 v27, 31, v26
	v_lshl_add_u64 v[24:25], v[4:5], 0, s[12:13]
	v_lshlrev_b64 v[28:29], 11, v[26:27]
	s_waitcnt lgkmcnt(6)
	v_cvt_pk_bf16_f32 v4, v10, v8
	s_waitcnt lgkmcnt(4)
	v_cvt_pk_bf16_f32 v5, v12, v14
	s_waitcnt lgkmcnt(2)
	v_cvt_pk_bf16_f32 v6, v16, v18
	s_waitcnt lgkmcnt(0)
	v_cvt_pk_bf16_f32 v7, v20, v22
	v_lshl_add_u64 v[28:29], v[24:25], 0, v[28:29]
	v_add_u32_e32 v8, 8, v26
	global_store_dwordx4 v[28:29], v[4:7], off
	s_nop 1
	v_cvt_pk_bf16_f32 v4, v11, v9
	v_ashrrev_i32_e32 v9, 31, v8
	v_cvt_pk_bf16_f32 v5, v13, v15
	v_cvt_pk_bf16_f32 v6, v17, v19
	v_cvt_pk_bf16_f32 v7, v21, v23
	v_lshlrev_b64 v[8:9], 11, v[8:9]
	ds_read2_b32 v[10:11], v2 offset0:49 offset1:57
	ds_read2_b32 v[12:13], v2 offset0:16 offset1:24
	ds_read2_b32 v[14:15], v2 offset0:82 offset1:90
	ds_read2_b32 v[16:17], v2 offset0:115 offset1:123
	ds_read2_b32 v[18:19], v2 offset0:148 offset1:156
	ds_read2_b32 v[20:21], v2 offset0:181 offset1:189
	ds_read2_b32 v[22:23], v2 offset0:214 offset1:222
	ds_read2_b32 v[28:29], v2 offset0:247 offset1:255
	v_lshl_add_u64 v[8:9], v[24:25], 0, v[8:9]
	global_store_dwordx4 v[8:9], v[4:7], off
	v_add_u32_e32 v8, 16, v26
	v_ashrrev_i32_e32 v9, 31, v8
	v_lshlrev_b64 v[8:9], 11, v[8:9]
	s_waitcnt lgkmcnt(6)
	v_cvt_pk_bf16_f32 v4, v12, v10
	s_waitcnt lgkmcnt(4)
	v_cvt_pk_bf16_f32 v5, v14, v16
	s_waitcnt lgkmcnt(2)
	v_cvt_pk_bf16_f32 v6, v18, v20
	s_waitcnt lgkmcnt(0)
	v_cvt_pk_bf16_f32 v7, v22, v28
	v_lshl_add_u64 v[8:9], v[24:25], 0, v[8:9]
	global_store_dwordx4 v[8:9], v[4:7], off
	v_add_u32_e32 v8, 24, v26
	v_ashrrev_i32_e32 v9, 31, v8
	v_lshlrev_b64 v[8:9], 11, v[8:9]
	v_cvt_pk_bf16_f32 v4, v13, v11
	v_cvt_pk_bf16_f32 v5, v15, v17
	v_cvt_pk_bf16_f32 v6, v19, v21
	v_cvt_pk_bf16_f32 v7, v23, v29
	v_lshl_add_u64 v[8:9], v[24:25], 0, v[8:9]
	global_store_dwordx4 v[8:9], v[4:7], off
	s_waitcnt lgkmcnt(0)
